# rmsnorm phases: 64-lane sum by DPP adds + lane reads instead of six LDS bpermute round trips
# speedup vs baseline: 1.0114x; 1.0023x over previous
; __device__ __forceinline__ void phase_norm(const Params& p, int l, int which, int nrows) {
;     ...
;   for (int r = r0; r < r1; ++r) {
;     const float* xr = xrow_ptr(p, from_input, r);
;     const int bi = mod_idx(r);
;     if (bi != cur_bi) {
;       const float* sh = mods_ptr(p, l, bi, which * 3);
; #pragma unroll
;       for (int i = 0; i < 4; ++i) { s4[i] = *(const float4*)(sh + i * 256 + lane * 4); c4[i] = *(const float4*)(sh + 1024 + i * 256 + lane * 4); }
;       cur_bi = bi;
;     }
;     float4 v[4];
;     float ss = 0.f;
; #pragma unroll
;     for (int i = 0; i < 4; ++i) {
;       v[i] = *(const float4*)(xr + i * 256 + lane * 4);
;       ss += v[i].x * v[i].x + v[i].y * v[i].y + v[i].z * v[i].z + v[i].w * v[i].w;
;     }
;     ss = wave_sum(ss);
;     const float rstd = rsqrtf(ss * (1.f / 1024.f) + 1e-6f);
; #pragma unroll
;     for (int i = 0; i < 4; ++i) {
;       const int c = i * 256 + lane * 4;
;       const float y0 = (v[i].x * rstd * g4[i].x) * (1.f + c4[i].x) + s4[i].x;
;       const float y1 = (v[i].y * rstd * g4[i].y) * (1.f + c4[i].y) + s4[i].y;
;       const float y2 = (v[i].z * rstd * g4[i].z) * (1.f + c4[i].z) + s4[i].z;
;       const float y3 = (v[i].w * rstd * g4[i].w) * (1.f + c4[i].w) + s4[i].w;
;       u32x2 o; o.x = pack2(y0, y1); o.y = pack2(y2, y3);
;       *(u32x2*)(H + (size_t)r * DM + c) = o;
;     }
.LBB0_334:
	s_or_b64 exec, exec, s[36:37]
	v_lshlrev_b64 v[58:59], 12, v[58:59]
	v_lshl_add_u64 v[56:57], v[56:57], 0, v[58:59]
	v_lshl_add_u64 v[76:77], v[56:57], 0, v[0:1]
	global_load_dwordx4 v[56:59], v[76:77], off
	global_load_dwordx4 v[68:71], v[76:77], off offset:1024
	global_load_dwordx4 v[72:75], v[76:77], off offset:2048
	s_nop 0
	global_load_dwordx4 v[76:79], v[76:77], off offset:3072
	v_lshl_add_u64 v[50:51], v[50:51], 0, 1
	v_cmp_ge_i32_e64 s[40:41], v50, v53
	s_mov_b64 s[36:37], 0x800
	s_or_b64 s[28:29], s[40:41], s[28:29]
	s_waitcnt vmcnt(3)
	v_mov_b32_e32 v86, v57
	s_waitcnt vmcnt(2)
	v_mov_b32_e32 v87, v69
	v_mov_b32_e32 v84, v56
	v_mov_b32_e32 v85, v68
	s_waitcnt vmcnt(1)
	v_mov_b32_e32 v140, v73
	s_waitcnt vmcnt(0)
	v_mov_b32_e32 v141, v77
	v_pk_mul_f32 v[86:87], v[86:87], v[86:87]
	v_mov_b32_e32 v80, v58
	v_mov_b32_e32 v81, v70
	v_mov_b32_e32 v138, v72
	v_mov_b32_e32 v139, v76
	v_pk_mul_f32 v[140:141], v[140:141], v[140:141]
	v_pk_fma_f32 v[84:85], v[84:85], v[84:85], v[86:87]
	v_mov_b32_e32 v82, v59
	v_mov_b32_e32 v83, v71
	v_mov_b32_e32 v88, v74
	v_mov_b32_e32 v89, v78
	v_pk_fma_f32 v[86:87], v[138:139], v[138:139], v[140:141]
	v_pk_fma_f32 v[80:81], v[80:81], v[80:81], v[84:85]
	v_mov_b32_e32 v136, v75
	v_mov_b32_e32 v137, v79
	v_pk_fma_f32 v[84:85], v[88:89], v[88:89], v[86:87]
	v_pk_fma_f32 v[80:81], v[82:83], v[82:83], v[80:81]
	v_pk_fma_f32 v[82:83], v[136:137], v[136:137], v[84:85]
	v_add_f32_e32 v0, v80, v81
	v_add_f32_e32 v0, v0, v82
	v_add_f32_e32 v0, v0, v83
	v_pk_add_f32 v[80:81], v[38:39], 1.0 op_sel_hi:[1,0]
	v_pk_add_f32 v[82:83], v[40:41], 1.0 op_sel_hi:[1,0]
	v_pk_add_f32 v[84:85], v[26:27], 1.0 op_sel_hi:[1,0]
	v_pk_add_f32 v[86:87], v[28:29], 1.0 op_sel_hi:[1,0]
	v_pk_add_f32 v[88:89], v[30:31], 1.0 op_sel_hi:[1,0]
	v_pk_add_f32 v[136:137], v[32:33], 1.0 op_sel_hi:[1,0]
	v_pk_add_f32 v[138:139], v[42:43], 1.0 op_sel_hi:[1,0]
	v_pk_add_f32 v[140:141], v[44:45], 1.0 op_sel_hi:[1,0]
	s_nop 1
	v_add_f32_dpp v0, v0, v0 quad_perm:[1,0,3,2] row_mask:0xf bank_mask:0xf
	s_nop 1
	v_add_f32_dpp v0, v0, v0 quad_perm:[2,3,0,1] row_mask:0xf bank_mask:0xf
	s_nop 1
	v_add_f32_dpp v0, v0, v0 row_half_mirror row_mask:0xf bank_mask:0xf
	s_nop 1
	v_add_f32_dpp v0, v0, v0 row_mirror row_mask:0xf bank_mask:0xf
	s_nop 1
	v_readlane_b32 vcc_lo, v0, 0
	v_readlane_b32 vcc_hi, v0, 16
	s_nop 1
	v_mov_b32_e32 v67, vcc_lo
	v_add_f32_e32 v67, vcc_hi, v67
	v_readlane_b32 vcc_lo, v0, 32
	v_readlane_b32 vcc_hi, v0, 48
	s_nop 1
	v_add_f32_e32 v67, vcc_lo, v67
	v_add_f32_e32 v0, vcc_hi, v67
	v_fmamk_f32 v0, v0, 0x3a800000, v174
	v_mul_f32_e32 v67, 0x4b800000, v0
	v_cmp_gt_f32_e32 vcc, s88, v0
	s_nop 1
	v_cndmask_b32_e32 v0, v0, v67, vcc
	v_rsq_f32_e32 v0, v0
	s_nop 0
	v_mul_f32_e32 v67, 0x45800000, v0
	v_cndmask_b32_e32 v0, v0, v67, vcc
	v_pk_mul_f32 v[56:57], v[56:57], v[0:1] op_sel_hi:[1,0]
	v_pk_mul_f32 v[58:59], v[58:59], v[0:1] op_sel_hi:[1,0]
	v_pk_mul_f32 v[68:69], v[68:69], v[0:1] op_sel_hi:[1,0]
	v_pk_mul_f32 v[70:71], v[70:71], v[0:1] op_sel_hi:[1,0]
	v_pk_mul_f32 v[72:73], v[72:73], v[0:1] op_sel_hi:[1,0]
	v_pk_mul_f32 v[74:75], v[74:75], v[0:1] op_sel_hi:[1,0]
	v_pk_mul_f32 v[76:77], v[76:77], v[0:1] op_sel_hi:[1,0]
	v_pk_mul_f32 v[78:79], v[78:79], v[0:1] op_sel_hi:[1,0]
	v_pk_mul_f32 v[56:57], v[2:3], v[56:57]
	v_pk_mul_f32 v[58:59], v[4:5], v[58:59]
	v_pk_mul_f32 v[68:69], v[6:7], v[68:69]
	v_pk_mul_f32 v[70:71], v[8:9], v[70:71]
	v_pk_mul_f32 v[72:73], v[10:11], v[72:73]
	v_pk_mul_f32 v[74:75], v[12:13], v[74:75]
	v_pk_mul_f32 v[76:77], v[14:15], v[76:77]
	v_pk_mul_f32 v[78:79], v[16:17], v[78:79]
	v_pk_fma_f32 v[56:57], v[80:81], v[56:57], v[18:19]
	v_pk_fma_f32 v[58:59], v[82:83], v[58:59], v[20:21]
	v_pk_fma_f32 v[68:69], v[84:85], v[68:69], v[22:23]
	v_pk_fma_f32 v[70:71], v[86:87], v[70:71], v[24:25]
	v_pk_fma_f32 v[72:73], v[88:89], v[72:73], v[34:35]
	v_pk_fma_f32 v[74:75], v[136:137], v[74:75], v[36:37]
	v_pk_fma_f32 v[76:77], v[138:139], v[76:77], v[46:47]
	v_pk_fma_f32 v[78:79], v[140:141], v[78:79], v[48:49]
	v_cvt_pk_bf16_f32 v56, v56, v57
	v_cvt_pk_bf16_f32 v57, v58, v59
	v_cvt_pk_bf16_f32 v58, v68, v69
	v_cvt_pk_bf16_f32 v59, v70, v71
	v_cvt_pk_bf16_f32 v68, v72, v73
	v_cvt_pk_bf16_f32 v69, v74, v75
	v_cvt_pk_bf16_f32 v70, v76, v77
	v_cvt_pk_bf16_f32 v71, v78, v79
	global_store_dwordx2 v[54:55], v[56:57], off
	global_store_dwordx2 v[54:55], v[58:59], off offset:512
	global_store_dwordx2 v[54:55], v[68:69], off offset:1024
	global_store_dwordx2 v[54:55], v[70:71], off offset:1536
	v_lshl_add_u64 v[54:55], v[54:55], 0, s[36:37]
	s_andn2_b64 exec, exec, s[28:29]
	s_cbranch_execz .LBB0_347

; __device__ __forceinline__ void phase_final_norm(const Params& p) {
;     ...
;   for (int r = blockIdx.x * 4 + (tidq >> 6); r < NLAT; r += gridDim.x * 4) {
;     float* xr = p.out + (size_t)r * DM;
;     float4 v[4];
;     float ss = 0.f;
; #pragma unroll
;     for (int i = 0; i < 4; ++i) {
;       v[i] = *(const float4*)(xr + i * 256 + lane * 4);
;       ss += v[i].x * v[i].x + v[i].y * v[i].y + v[i].z * v[i].z + v[i].w * v[i].w;
;     }
;     ss = wave_sum(ss);
;     const float rstd = rsqrtf(ss * (1.f / 1024.f) + 1e-6f);
; #pragma unroll
;     for (int i = 0; i < 4; ++i) {
;       float4 o; o.x = v[i].x * rstd * g4[i].x; o.y = v[i].y * rstd * g4[i].y; o.z = v[i].z * rstd * g4[i].z; o.w = v[i].w * rstd * g4[i].w;
;       *(float4*)(xr + i * 256 + lane * 4) = o;
;     }
;   }
.LBB0_369:
	v_ashrrev_i32_e32 v17, 31, v16
	v_lshlrev_b64 v[28:29], 12, v[16:17]
	v_lshl_add_u64 v[44:45], v[18:19], 0, v[28:29]
	global_load_dwordx4 v[28:31], v[44:45], off
	global_load_dwordx4 v[32:35], v[44:45], off offset:1024
	global_load_dwordx4 v[36:39], v[44:45], off offset:2048
	global_load_dwordx4 v[40:43], v[44:45], off offset:3072
	v_add_u32_e32 v16, s38, v16
	v_cmp_lt_i32_e64 s[0:1], s5, v16
	s_or_b64 s[2:3], s[0:1], s[2:3]
	s_waitcnt vmcnt(3)
	v_mov_b32_e32 v48, v29
	s_waitcnt vmcnt(2)
	v_mov_b32_e32 v49, v33
	v_mov_b32_e32 v46, v28
	v_mov_b32_e32 v47, v32
	s_waitcnt vmcnt(1)
	v_mov_b32_e32 v56, v37
	s_waitcnt vmcnt(0)
	v_mov_b32_e32 v57, v41
	v_pk_mul_f32 v[48:49], v[48:49], v[48:49]
	v_mov_b32_e32 v50, v30
	v_mov_b32_e32 v51, v34
	v_mov_b32_e32 v54, v36
	v_mov_b32_e32 v55, v40
	v_pk_mul_f32 v[56:57], v[56:57], v[56:57]
	v_pk_fma_f32 v[46:47], v[46:47], v[46:47], v[48:49]
	v_mov_b32_e32 v52, v31
	v_mov_b32_e32 v53, v35
	v_mov_b32_e32 v58, v38
	v_mov_b32_e32 v59, v42
	v_pk_fma_f32 v[48:49], v[54:55], v[54:55], v[56:57]
	v_pk_fma_f32 v[46:47], v[50:51], v[50:51], v[46:47]
	v_mov_b32_e32 v60, v39
	v_mov_b32_e32 v61, v43
	v_pk_fma_f32 v[48:49], v[58:59], v[58:59], v[48:49]
	v_pk_fma_f32 v[46:47], v[52:53], v[52:53], v[46:47]
	v_pk_fma_f32 v[48:49], v[60:61], v[60:61], v[48:49]
	v_add_f32_e32 v17, v46, v47
	v_add_f32_e32 v17, v17, v48
	v_add_f32_e32 v17, v17, v49
	s_nop 1
	v_add_f32_dpp v17, v17, v17 quad_perm:[1,0,3,2] row_mask:0xf bank_mask:0xf
	s_nop 1
	v_add_f32_dpp v17, v17, v17 quad_perm:[2,3,0,1] row_mask:0xf bank_mask:0xf
	s_nop 1
	v_add_f32_dpp v17, v17, v17 row_half_mirror row_mask:0xf bank_mask:0xf
	s_nop 1
	v_add_f32_dpp v17, v17, v17 row_mirror row_mask:0xf bank_mask:0xf
	s_nop 1
	v_readlane_b32 vcc_lo, v17, 0
	v_readlane_b32 vcc_hi, v17, 16
	s_nop 1
	v_mov_b32_e32 v27, vcc_lo
	v_add_f32_e32 v27, vcc_hi, v27
	v_readlane_b32 vcc_lo, v17, 32
	v_readlane_b32 vcc_hi, v17, 48
	s_nop 1
	v_add_f32_e32 v27, vcc_lo, v27
	v_add_f32_e32 v17, vcc_hi, v27
	v_fmamk_f32 v17, v17, 0x3a800000, v26
	v_mul_f32_e32 v27, 0x4b800000, v17
	v_cmp_gt_f32_e32 vcc, s4, v17
	s_nop 1
	v_cndmask_b32_e32 v17, v17, v27, vcc
	v_rsq_f32_e32 v17, v17
	s_nop 0
	v_mul_f32_e32 v27, 0x45800000, v17
	v_cndmask_b32_e32 v46, v17, v27, vcc
	v_pk_mul_f32 v[28:29], v[28:29], v[46:47] op_sel_hi:[1,0]
	v_pk_mul_f32 v[30:31], v[30:31], v[46:47] op_sel_hi:[1,0]
	v_pk_mul_f32 v[32:33], v[32:33], v[46:47] op_sel_hi:[1,0]
	v_pk_mul_f32 v[34:35], v[34:35], v[46:47] op_sel_hi:[1,0]
	v_pk_mul_f32 v[36:37], v[36:37], v[46:47] op_sel_hi:[1,0]
	v_pk_mul_f32 v[38:39], v[38:39], v[46:47] op_sel_hi:[1,0]
	v_pk_mul_f32 v[40:41], v[40:41], v[46:47] op_sel_hi:[1,0]
	v_pk_mul_f32 v[42:43], v[42:43], v[46:47] op_sel_hi:[1,0]
	v_pk_mul_f32 v[28:29], v[0:1], v[28:29]
	v_pk_mul_f32 v[30:31], v[2:3], v[30:31]
	v_pk_mul_f32 v[32:33], v[4:5], v[32:33]
	v_pk_mul_f32 v[34:35], v[6:7], v[34:35]
	v_pk_mul_f32 v[36:37], v[8:9], v[36:37]
	v_pk_mul_f32 v[38:39], v[10:11], v[38:39]
	v_pk_mul_f32 v[40:41], v[12:13], v[40:41]
	v_pk_mul_f32 v[42:43], v[14:15], v[42:43]
	global_store_dwordx4 v[44:45], v[28:31], off
	global_store_dwordx4 v[44:45], v[32:35], off offset:1024
	global_store_dwordx4 v[44:45], v[36:39], off offset:2048
	global_store_dwordx4 v[44:45], v[40:43], off offset:3072
	s_andn2_b64 exec, exec, s[2:3]
	s_cbranch_execnz .LBB0_369
